# phase 0 w2/a2 transposes: 8 consecutive k per thread, loads in flight together, one 16-byte store instead of 8 scattered 2-byte stores
# baseline (speedup 1.0000x reference)
.LBB0_849:
	s_or_b64 exec, exec, s[4:5]
	s_mov_b32 s4, 0x200000
	v_cmp_gt_i32_e32 vcc, s4, v2
	s_and_saveexec_b64 s[4:5], vcc
	s_cbranch_execz .LBB0_860
	s_load_dwordx2 s[40:41], s[0:1], 0x98
	s_load_dwordx2 s[8:9], s[0:1], 0xb0
	s_mov_b32 s6, 0
	v_mov_b32_e32 v17, 0
	s_waitcnt lgkmcnt(0)
.Lcvt_loop:
	s_lshl_b32 s7, s6, 17
	v_add_u32_e32 v3, s7, v2
	v_and_b32_e32 v4, 0x7ff, v3
	v_lshrrev_b32_e32 v5, 11, v3
	v_and_b32_e32 v6, 31, v5
	v_lshrrev_b32_e32 v7, 5, v5
	v_and_b32_e32 v8, 1, v7
	v_mov_b32_e32 v10, s40
	v_mov_b32_e32 v11, s41
	v_mov_b32_e32 v12, s8
	v_mov_b32_e32 v13, s9
	v_cmp_lt_u32_e32 vcc, 1, v7
	v_mul_u32_u24_e32 v14, 0xc0000, v8
	v_lshl_add_u32 v14, v4, 2, v14
	v_cndmask_b32_e32 v10, v10, v12, vcc
	v_cndmask_b32_e32 v11, v11, v13, vcc
	v_add_co_u32_e32 v10, vcc, v10, v14
	v_lshlrev_b32_e32 v15, 3, v6
	v_mul_u32_u24_e32 v9, 0x60, v8
	v_addc_co_u32_e32 v11, vcc, 0, v11, vcc
	v_sub_u32_e32 v15, v15, v9
	v_add_u32_e32 v16, 0, v15
	v_max_i32_e32 v16, 0, v16
	v_min_i32_e32 v16, 0x5f, v16
	v_lshlrev_b32_e32 v16, 13, v16
	v_lshl_add_u64 v[18:19], v[16:17], 0, v[10:11]
	global_load_dword v20, v[18:19], off
	v_add_u32_e32 v16, 1, v15
	v_max_i32_e32 v16, 0, v16
	v_min_i32_e32 v16, 0x5f, v16
	v_lshlrev_b32_e32 v16, 13, v16
	v_lshl_add_u64 v[18:19], v[16:17], 0, v[10:11]
	global_load_dword v21, v[18:19], off
	v_add_u32_e32 v16, 2, v15
	v_max_i32_e32 v16, 0, v16
	v_min_i32_e32 v16, 0x5f, v16
	v_lshlrev_b32_e32 v16, 13, v16
	v_lshl_add_u64 v[18:19], v[16:17], 0, v[10:11]
	global_load_dword v22, v[18:19], off
	v_add_u32_e32 v16, 3, v15
	v_max_i32_e32 v16, 0, v16
	v_min_i32_e32 v16, 0x5f, v16
	v_lshlrev_b32_e32 v16, 13, v16
	v_lshl_add_u64 v[18:19], v[16:17], 0, v[10:11]
	global_load_dword v23, v[18:19], off
	v_add_u32_e32 v16, 4, v15
	v_max_i32_e32 v16, 0, v16
	v_min_i32_e32 v16, 0x5f, v16
	v_lshlrev_b32_e32 v16, 13, v16
	v_lshl_add_u64 v[18:19], v[16:17], 0, v[10:11]
	global_load_dword v24, v[18:19], off
	v_add_u32_e32 v16, 5, v15
	v_max_i32_e32 v16, 0, v16
	v_min_i32_e32 v16, 0x5f, v16
	v_lshlrev_b32_e32 v16, 13, v16
	v_lshl_add_u64 v[18:19], v[16:17], 0, v[10:11]
	global_load_dword v25, v[18:19], off
	v_add_u32_e32 v16, 6, v15
	v_max_i32_e32 v16, 0, v16
	v_min_i32_e32 v16, 0x5f, v16
	v_lshlrev_b32_e32 v16, 13, v16
	v_lshl_add_u64 v[18:19], v[16:17], 0, v[10:11]
	global_load_dword v26, v[18:19], off
	v_add_u32_e32 v16, 7, v15
	v_max_i32_e32 v16, 0, v16
	v_min_i32_e32 v16, 0x5f, v16
	v_lshlrev_b32_e32 v16, 13, v16
	v_lshl_add_u64 v[18:19], v[16:17], 0, v[10:11]
	global_load_dword v27, v[18:19], off
	s_waitcnt vmcnt(0)
	v_add_u32_e32 v16, 0, v15
	v_cmp_gt_u32_e32 vcc, 0x60, v16
	s_nop 1
	v_cndmask_b32_e32 v20, 0, v20, vcc
	v_add_u32_e32 v16, 1, v15
	v_cmp_gt_u32_e32 vcc, 0x60, v16
	s_nop 1
	v_cndmask_b32_e32 v21, 0, v21, vcc
	v_add_u32_e32 v16, 2, v15
	v_cmp_gt_u32_e32 vcc, 0x60, v16
	s_nop 1
	v_cndmask_b32_e32 v22, 0, v22, vcc
	v_add_u32_e32 v16, 3, v15
	v_cmp_gt_u32_e32 vcc, 0x60, v16
	s_nop 1
	v_cndmask_b32_e32 v23, 0, v23, vcc
	v_add_u32_e32 v16, 4, v15
	v_cmp_gt_u32_e32 vcc, 0x60, v16
	s_nop 1
	v_cndmask_b32_e32 v24, 0, v24, vcc
	v_add_u32_e32 v16, 5, v15
	v_cmp_gt_u32_e32 vcc, 0x60, v16
	s_nop 1
	v_cndmask_b32_e32 v25, 0, v25, vcc
	v_add_u32_e32 v16, 6, v15
	v_cmp_gt_u32_e32 vcc, 0x60, v16
	s_nop 1
	v_cndmask_b32_e32 v26, 0, v26, vcc
	v_add_u32_e32 v16, 7, v15
	v_cmp_gt_u32_e32 vcc, 0x60, v16
	s_nop 1
	v_cndmask_b32_e32 v27, 0, v27, vcc
	v_cvt_pk_bf16_f32 v28, v20, v21
	v_cvt_pk_bf16_f32 v29, v22, v23
	v_cvt_pk_bf16_f32 v30, v24, v25
	v_cvt_pk_bf16_f32 v31, v26, v27
	v_lshlrev_b32_e32 v32, 20, v7
	v_add_u32_e32 v32, 0x2300000, v32
	v_lshl_add_u32 v32, v4, 9, v32
	v_lshl_add_u32 v32, v6, 4, v32
	global_store_dwordx4 v32, v[28:31], s[46:47]
	s_add_i32 s6, s6, 1
	s_cmp_lt_u32 s6, 2
	s_cbranch_scc1 .Lcvt_loop
